# NA loop: stop draining the output stores at the top of every iteration (vmcnt(4)), one full wait at loop entry
# speedup vs baseline: 1.0051x; 1.0051x over previous
; #define NA_PUT(row, v) do { unsigned char* rp_ = Vl + ((row) % 11) * 8192 + (col & 3) * 2; _Pragma("unroll") for (int i_ = 0; i_ < 8; ++i_) { const int d_ = 8 * c16 + i_; const unsigned wd_ = (v)[i_ >> 1]; \
;         *(unsigned short*)(rp_ + d_ * 128 + (((col >> 2) ^ (d_ & 15)) << 3)) = (unsigned short)((i_ & 1) ? (wd_ >> 16) : (wd_ & 0xffffu)); } } while (0)
; __device__ __forceinline__ void na_wg_item(const Params& p, int wgi, unsigned char* lds, const float* rpl) {
;     ...
;     { const int h0 = NA_HI(0), h1 = NA_HI(1);
; #pragma unroll
;       for (int n = 0; n < 2; ++n) if (h0 + n < h1) pre[n] = *(const u32x4*)(vU + (size_t)((h0 + n) * 64 * 3072 + vl)); }
; #pragma unroll 1
;     for (int it = 0; it < 16; ++it) {
;         __syncthreads();
;         const int h0 = NA_HI(it), h1 = NA_HI(it + 1), h2 = NA_HI(it + 2);
; #pragma unroll
;         for (int n = 0; n < 2; ++n) if (h0 + n < h1) NA_PUT(h0 + n, pre[n]);
; #pragma unroll
;         for (int n = 0; n < 2; ++n) if (h1 + n < h2) pre[n] = *(const u32x4*)(vU + (size_t)((h1 + n) * 64 * 3072 + vl));
;         na_item(p, b, hd, r0 + 2 * it + (wave >> 2), wave & 3, lane, rpl, Vl);
.LBB0_328:
	s_ashr_i32 s27, s26, 31
	s_lshl_b64 s[26:27], s[26:27], 12
	s_lshl_b32 s36, s29, 6
	v_lshl_or_b32 v74, s28, 11, v122
	s_mulk_i32 s29, 0x744
	v_lshl_add_u64 v[8:9], v[72:73], 0, s[26:27]
	s_add_i32 s60, s29, 0
	s_lshl_b32 s28, s36, 1
	s_mov_b32 s29, s3
	v_lshl_add_u64 v[8:9], v[8:9], 0, v[74:75]
	s_lshr_b32 s2, s38, 1
	v_lshl_add_u64 v[82:83], v[76:77], 0, s[28:29]
	v_mad_u64_u32 v[84:85], s[28:29], v8, s40, v[78:79]
	s_and_b32 s2, s2, 15
	v_mad_i32_i24 v85, v9, s40, v85
	v_lshlrev_b64 v[8:9], 11, v[8:9]
	v_add_u32_e32 v147, s58, v106
	v_subrev_u32_e32 v148, s58, v121
	s_lshl_b32 s2, s2, 7
	s_or_b32 s61, s59, 1
	v_lshl_add_u64 v[86:87], v[80:81], 0, v[8:9]
	s_mov_b32 s28, 0
	s_waitcnt vmcnt(0)
	s_branch .LBB0_330

; #define NA_PUT(row, v) do { unsigned char* rp_ = Vl + ((row) % 11) * 8192 + (col & 3) * 2; _Pragma("unroll") for (int i_ = 0; i_ < 8; ++i_) { const int d_ = 8 * c16 + i_; const unsigned wd_ = (v)[i_ >> 1]; \
;         *(unsigned short*)(rp_ + d_ * 128 + (((col >> 2) ^ (d_ & 15)) << 3)) = (unsigned short)((i_ & 1) ? (wd_ >> 16) : (wd_ & 0xffffu)); } } while (0)
; __device__ __forceinline__ void na_wg_item(const Params& p, int wgi, unsigned char* lds, const float* rpl) {
;     ...
;     __syncthreads();
;     const int lo = min(max(r0 - 4, 0), 56);
;     for (int row = lo; row < NA_HI(0); ++row) { const u32x4 v = *(const u32x4*)(vU + (size_t)(row * 64 * 3072 + vl)); NA_PUT(row, v); }
;     u32x4 pre[2] = {{0u, 0u, 0u, 0u}, {0u, 0u, 0u, 0u}};
;     { const int h0 = NA_HI(0), h1 = NA_HI(1);
; #pragma unroll
;       for (int n = 0; n < 2; ++n) if (h0 + n < h1) pre[n] = *(const u32x4*)(vU + (size_t)((h0 + n) * 64 * 3072 + vl)); }
; #pragma unroll 1
;     for (int it = 0; it < 16; ++it) {
;         __syncthreads();
;         const int h0 = NA_HI(it), h1 = NA_HI(it + 1), h2 = NA_HI(it + 2);
; #pragma unroll
;         for (int n = 0; n < 2; ++n) if (h0 + n < h1) NA_PUT(h0 + n, pre[n]);
; #pragma unroll
;         for (int n = 0; n < 2; ++n) if (h1 + n < h2) pre[n] = *(const u32x4*)(vU + (size_t)((h1 + n) * 64 * 3072 + vl));
.LBB0_330:
	s_max_i32 s29, s58, 3
	s_add_i32 s62, s28, 1
	s_add_i32 s36, s29, -3
	s_min_u32 s29, s62, 15
	s_lshl_b32 s29, s29, 1
	s_or_b32 s29, s29, s59
	s_max_i32 s63, s29, 3
	s_add_i32 s63, s63, -3
	s_min_u32 s65, s36, 56
	s_min_u32 s29, s63, 56
	s_cmp_ge_u32 s36, s29
	s_waitcnt lgkmcnt(0)
	s_barrier
	s_cbranch_scc1 .LBB0_332
	s_add_i32 s36, s65, 8
	s_mul_i32 s37, s36, 0xbb
	s_bfe_u32 s37, s37, 0x5000b
	s_mul_i32 s37, s37, 11
	s_sub_i32 s36, s36, s37
	s_and_b32 s36, s36, 0xff
	v_lshl_add_u32 v8, s36, 13, v89
	v_add3_u32 v9, v8, v90, v91
	s_waitcnt vmcnt(4)
	ds_write_b16 v9, v4 offset:32768
	v_add3_u32 v9, v8, v92, v93
	ds_write_b16_d16_hi v9, v4 offset:32768
	v_add3_u32 v9, v8, v94, v95
	ds_write_b16 v9, v5 offset:32768
	v_add3_u32 v9, v8, v96, v97
	ds_write_b16_d16_hi v9, v5 offset:32768
	v_add3_u32 v9, v8, v98, v99
	ds_write_b16 v9, v6 offset:32768
	v_add3_u32 v9, v8, v100, v101
	ds_write_b16_d16_hi v9, v6 offset:32768
	v_add3_u32 v9, v8, v102, v103
	v_add3_u32 v8, v8, v104, v105
	ds_write_b16 v9, v7 offset:32768
	ds_write_b16_d16_hi v8, v7 offset:32768
.LBB0_332:
	s_add_i32 s64, s29, 8
	s_add_i32 s65, s65, 9
	s_cmp_ge_u32 s65, s64
	s_cbranch_scc1 .LBB0_334
	s_mul_i32 s36, s65, 0xbb
	s_lshr_b32 s36, s36, 11
	s_mul_i32 s36, s36, 11
	s_sub_i32 s36, s65, s36
	s_and_b32 s36, s36, 0xff
	v_lshl_add_u32 v8, s36, 13, v89
	v_add3_u32 v9, v8, v90, v91
	s_waitcnt vmcnt(4)
	ds_write_b16 v9, v0 offset:32768
	v_add3_u32 v9, v8, v92, v93
	ds_write_b16_d16_hi v9, v0 offset:32768
	v_add3_u32 v9, v8, v94, v95
	ds_write_b16 v9, v1 offset:32768
	v_add3_u32 v9, v8, v96, v97
	ds_write_b16_d16_hi v9, v1 offset:32768
	v_add3_u32 v9, v8, v98, v99
	ds_write_b16 v9, v2 offset:32768
	v_add3_u32 v9, v8, v100, v101
	ds_write_b16_d16_hi v9, v2 offset:32768
	v_add3_u32 v9, v8, v102, v103
	v_add3_u32 v8, v8, v104, v105
	ds_write_b16 v9, v3 offset:32768
	ds_write_b16_d16_hi v8, v3 offset:32768
.LBB0_334:
	s_min_u32 s28, s28, 13
	s_lshl_b32 s28, s28, 1
	s_or_b32 s28, s28, s61
	s_min_u32 s28, s28, 56
	s_cmp_lt_u32 s63, s28
	s_cbranch_scc0 .LBB0_336
	s_mul_i32 s64, s64, 0x30000
	s_waitcnt vmcnt(4)
	v_add_lshl_u32 v4, s64, v88, 1
	global_load_dwordx4 v[4:7], v4, s[24:25]
.LBB0_336:
	s_add_i32 s36, s28, 8
	s_add_i32 s28, s29, 9
	s_cmp_ge_u32 s28, s36
	s_cbranch_scc1 .LBB0_338
	s_mul_i32 s28, s28, 0x30000
	s_waitcnt vmcnt(4)
	v_add_lshl_u32 v0, s28, v88, 1
	global_load_dwordx4 v[0:3], v0, s[24:25]
